# LDS-DMA attention loop: V fragment LDS reads issued one per MFMA gap instead of a burst of four at each 16-key step
# speedup vs baseline: 1.0254x; 1.0254x over previous
.Lattn_nf_loop:
	ds_read_b128 v[98:101], v82 offset:0
	ds_read_b128 v[102:105], v83 offset:0
	ds_read_b128 v[106:109], v84 offset:0
	ds_read_b128 v[110:113], v85 offset:0
	s_and_b32 s10, s15, 1
	s_xor_b32 s10, s10, 1
	s_lshl_b32 s10, s10, 15
	s_add_i32 s10, s10, s11
	s_add_i32 s6, s10, 0x10000
	s_waitcnt lgkmcnt(3)
	v_mfma_f32_32x32x16_bf16 v[138:153], v[98:101], v[10:13], 0
	ds_read_b128 v[98:101], v82 offset:8192
	s_add_i32 m0, s10, 0x0
	s_nop 0
	global_load_lds_dwordx4 v124, s[64:65]
	s_add_i32 m0, s10, 0x2000
	s_nop 0
	global_load_lds_dwordx4 v124, s[66:67]
	s_waitcnt lgkmcnt(3)
	v_mfma_f32_32x32x16_bf16 v[138:153], v[102:105], v[14:17], v[138:153]
	ds_read_b128 v[102:105], v83 offset:8192
	s_add_i32 m0, s10, 0x4000
	s_nop 0
	global_load_lds_dwordx4 v124, s[68:69]
	s_add_i32 m0, s10, 0x6000
	s_nop 0
	global_load_lds_dwordx4 v124, s[70:71]
	v_add_u32_e32 v124, s36, v124
	s_waitcnt lgkmcnt(3)
	v_mfma_f32_32x32x16_bf16 v[138:153], v[106:109], v[2:5], v[138:153]
	ds_read_b128 v[106:109], v84 offset:8192
	s_add_i32 m0, s6, 0x0
	s_nop 0
	global_load_lds_dwordx4 v125, s[72:73]
	s_add_i32 m0, s6, 0x2000
	s_nop 0
	global_load_lds_dwordx4 v125, s[74:75]
	s_waitcnt lgkmcnt(3)
	v_mfma_f32_32x32x16_bf16 v[138:153], v[110:113], v[6:9], v[138:153]
	ds_read_b128 v[110:113], v85 offset:8192
	s_add_i32 m0, s6, 0x4000
	s_nop 0
	global_load_lds_dwordx4 v125, s[76:77]
	s_add_i32 m0, s6, 0x6000
	s_nop 0
	global_load_lds_dwordx4 v125, s[78:79]
	v_add_u32_e32 v125, s38, v125
	s_waitcnt lgkmcnt(3)
	v_mfma_f32_32x32x16_bf16 v[154:169], v[98:101], v[10:13], 0
	ds_read_b128 v[98:101], v82 offset:16384
	ds_read_b128 v[128:131], v86 offset:0
	ds_read_b128 v[184:187], v86 offset:8192
	v_exp_f32_e32 v138, v138
	v_exp_f32_e32 v139, v139
	v_exp_f32_e32 v140, v140
	v_exp_f32_e32 v141, v141
	v_exp_f32_e32 v142, v142
	v_exp_f32_e32 v143, v143
	s_waitcnt lgkmcnt(5)
	v_mfma_f32_32x32x16_bf16 v[154:169], v[102:105], v[14:17], v[154:169]
	ds_read_b128 v[102:105], v83 offset:16384
	ds_read_b128 v[188:191], v86 offset:16384
	ds_read_b128 v[192:195], v86 offset:24576
	v_exp_f32_e32 v144, v144
	v_exp_f32_e32 v145, v145
	v_add_f32_e32 v122, v138, v122
	v_add_f32_e32 v122, v139, v122
	v_add_f32_e32 v122, v140, v122
	v_add_f32_e32 v122, v141, v122
	v_add_f32_e32 v122, v142, v122
	v_add_f32_e32 v122, v143, v122
	v_add_f32_e32 v122, v144, v122
	v_add_f32_e32 v122, v145, v122
	v_cvt_pk_bf16_f32 v114, v138, v139
	v_cvt_pk_bf16_f32 v115, v140, v141
	v_cvt_pk_bf16_f32 v116, v142, v143
	v_cvt_pk_bf16_f32 v117, v144, v145
	s_waitcnt lgkmcnt(7)
	v_mfma_f32_32x32x16_bf16 v[154:169], v[106:109], v[2:5], v[154:169]
	ds_read_b128 v[106:109], v84 offset:16384
	ds_read_b128 v[196:199], v87 offset:0
	v_exp_f32_e32 v146, v146
	v_exp_f32_e32 v147, v147
	s_waitcnt lgkmcnt(8)
	v_mfma_f32_32x32x16_bf16 v[154:169], v[110:113], v[6:9], v[154:169]
	ds_read_b128 v[110:113], v85 offset:16384
	ds_read_b128 v[216:219], v87 offset:8192
	v_exp_f32_e32 v148, v148
	v_exp_f32_e32 v149, v149
	s_waitcnt lgkmcnt(8)
	v_mfma_f32_32x32x16_bf16 v[18:33], v[128:131], v[114:117], v[18:33]
	v_exp_f32_e32 v150, v150
	v_exp_f32_e32 v151, v151
	s_waitcnt lgkmcnt(7)
	v_mfma_f32_32x32x16_bf16 v[34:49], v[184:187], v[114:117], v[34:49]
	ds_read_b128 v[200:203], v87 offset:16384
	v_exp_f32_e32 v152, v152
	v_exp_f32_e32 v153, v153
	s_waitcnt lgkmcnt(6)
	v_mfma_f32_32x32x16_bf16 v[50:65], v[188:191], v[114:117], v[50:65]
	ds_read_b128 v[204:207], v87 offset:24576
	v_add_f32_e32 v122, v146, v122
	v_add_f32_e32 v122, v147, v122
	v_add_f32_e32 v122, v148, v122
	v_add_f32_e32 v122, v149, v122
	s_waitcnt lgkmcnt(6)
	v_mfma_f32_32x32x16_bf16 v[66:81], v[192:195], v[114:117], v[66:81]
	v_add_f32_e32 v122, v150, v122
	v_add_f32_e32 v122, v151, v122
	v_add_f32_e32 v122, v152, v122
	v_add_f32_e32 v122, v153, v122
	v_cvt_pk_bf16_f32 v118, v146, v147
	v_cvt_pk_bf16_f32 v119, v148, v149
	v_cvt_pk_bf16_f32 v120, v150, v151
	v_cvt_pk_bf16_f32 v121, v152, v153
	v_mfma_f32_32x32x16_bf16 v[138:153], v[98:101], v[10:13], 0
	ds_read_b128 v[98:101], v82 offset:24576
	ds_read_b128 v[128:131], v88 offset:0
	v_exp_f32_e32 v154, v154
	v_exp_f32_e32 v155, v155
	v_mfma_f32_32x32x16_bf16 v[138:153], v[102:105], v[14:17], v[138:153]
	ds_read_b128 v[102:105], v83 offset:24576
	ds_read_b128 v[184:187], v88 offset:8192
	v_exp_f32_e32 v156, v156
	v_exp_f32_e32 v157, v157
	s_waitcnt lgkmcnt(8)
	v_mfma_f32_32x32x16_bf16 v[18:33], v[196:199], v[118:121], v[18:33]
	v_exp_f32_e32 v158, v158
	v_exp_f32_e32 v159, v159
	s_waitcnt lgkmcnt(6)
	v_mfma_f32_32x32x16_bf16 v[34:49], v[216:219], v[118:121], v[34:49]
	ds_read_b128 v[188:191], v88 offset:16384
	v_exp_f32_e32 v160, v160
	v_exp_f32_e32 v161, v161
	s_waitcnt lgkmcnt(6)
	v_mfma_f32_32x32x16_bf16 v[50:65], v[200:203], v[118:121], v[50:65]
	ds_read_b128 v[192:195], v88 offset:24576
	v_add_f32_e32 v122, v154, v122
	v_add_f32_e32 v122, v155, v122
	v_add_f32_e32 v122, v156, v122
	v_add_f32_e32 v122, v157, v122
	s_waitcnt lgkmcnt(6)
	v_mfma_f32_32x32x16_bf16 v[66:81], v[204:207], v[118:121], v[66:81]
	v_add_f32_e32 v122, v158, v122
	v_add_f32_e32 v122, v159, v122
	v_add_f32_e32 v122, v160, v122
	v_add_f32_e32 v122, v161, v122
	v_cvt_pk_bf16_f32 v114, v154, v155
	v_cvt_pk_bf16_f32 v115, v156, v157
	v_cvt_pk_bf16_f32 v116, v158, v159
	v_cvt_pk_bf16_f32 v117, v160, v161
	v_mfma_f32_32x32x16_bf16 v[138:153], v[106:109], v[2:5], v[138:153]
	ds_read_b128 v[106:109], v84 offset:24576
	ds_read_b128 v[196:199], v89 offset:0
	v_exp_f32_e32 v162, v162
	v_exp_f32_e32 v163, v163
	v_mfma_f32_32x32x16_bf16 v[138:153], v[110:113], v[6:9], v[138:153]
	ds_read_b128 v[110:113], v85 offset:24576
	ds_read_b128 v[216:219], v89 offset:8192
	v_exp_f32_e32 v164, v164
	v_exp_f32_e32 v165, v165
	s_waitcnt lgkmcnt(8)
	v_mfma_f32_32x32x16_bf16 v[18:33], v[128:131], v[114:117], v[18:33]
	v_exp_f32_e32 v166, v166
	v_exp_f32_e32 v167, v167
	s_waitcnt lgkmcnt(6)
	v_mfma_f32_32x32x16_bf16 v[34:49], v[184:187], v[114:117], v[34:49]
	ds_read_b128 v[200:203], v89 offset:16384
	v_exp_f32_e32 v168, v168
	v_exp_f32_e32 v169, v169
	s_waitcnt lgkmcnt(6)
	v_mfma_f32_32x32x16_bf16 v[50:65], v[188:191], v[114:117], v[50:65]
	ds_read_b128 v[204:207], v89 offset:24576
	v_add_f32_e32 v122, v162, v122
	v_add_f32_e32 v122, v163, v122
	v_add_f32_e32 v122, v164, v122
	v_add_f32_e32 v122, v165, v122
	s_waitcnt lgkmcnt(6)
	v_mfma_f32_32x32x16_bf16 v[66:81], v[192:195], v[114:117], v[66:81]
	v_add_f32_e32 v122, v166, v122
	v_add_f32_e32 v122, v167, v122
	v_add_f32_e32 v122, v168, v122
	v_add_f32_e32 v122, v169, v122
	v_cvt_pk_bf16_f32 v118, v162, v163
	v_cvt_pk_bf16_f32 v119, v164, v165
	v_cvt_pk_bf16_f32 v120, v166, v167
	v_cvt_pk_bf16_f32 v121, v168, v169
	v_mfma_f32_32x32x16_bf16 v[154:169], v[98:101], v[10:13], 0
	ds_read_b128 v[128:131], v90 offset:0
	v_exp_f32_e32 v138, v138
	v_exp_f32_e32 v139, v139
	v_mfma_f32_32x32x16_bf16 v[154:169], v[102:105], v[14:17], v[154:169]
	ds_read_b128 v[184:187], v90 offset:8192
	v_exp_f32_e32 v140, v140
	v_exp_f32_e32 v141, v141
	s_waitcnt lgkmcnt(6)
	v_mfma_f32_32x32x16_bf16 v[18:33], v[196:199], v[118:121], v[18:33]
	v_exp_f32_e32 v142, v142
	v_exp_f32_e32 v143, v143
	s_waitcnt lgkmcnt(4)
	v_mfma_f32_32x32x16_bf16 v[34:49], v[216:219], v[118:121], v[34:49]
	ds_read_b128 v[188:191], v90 offset:16384
	v_exp_f32_e32 v144, v144
	v_exp_f32_e32 v145, v145
	s_waitcnt lgkmcnt(4)
	v_mfma_f32_32x32x16_bf16 v[50:65], v[200:203], v[118:121], v[50:65]
	ds_read_b128 v[192:195], v90 offset:24576
	v_add_f32_e32 v122, v138, v122
	v_add_f32_e32 v122, v139, v122
	v_add_f32_e32 v122, v140, v122
	v_add_f32_e32 v122, v141, v122
	s_waitcnt lgkmcnt(4)
	v_mfma_f32_32x32x16_bf16 v[66:81], v[204:207], v[118:121], v[66:81]
	v_add_f32_e32 v122, v142, v122
	v_add_f32_e32 v122, v143, v122
	v_add_f32_e32 v122, v144, v122
	v_add_f32_e32 v122, v145, v122
	v_cvt_pk_bf16_f32 v114, v138, v139
	v_cvt_pk_bf16_f32 v115, v140, v141
	v_cvt_pk_bf16_f32 v116, v142, v143
	v_cvt_pk_bf16_f32 v117, v144, v145
	v_mfma_f32_32x32x16_bf16 v[154:169], v[106:109], v[2:5], v[154:169]
	ds_read_b128 v[196:199], v91 offset:0
	v_exp_f32_e32 v146, v146
	v_exp_f32_e32 v147, v147
	v_mfma_f32_32x32x16_bf16 v[154:169], v[110:113], v[6:9], v[154:169]
	ds_read_b128 v[216:219], v91 offset:8192
	v_exp_f32_e32 v148, v148
	v_exp_f32_e32 v149, v149
	s_waitcnt lgkmcnt(5)
	v_mfma_f32_32x32x16_bf16 v[18:33], v[128:131], v[114:117], v[18:33]
	v_exp_f32_e32 v150, v150
	v_exp_f32_e32 v151, v151
	s_waitcnt lgkmcnt(4)
	v_mfma_f32_32x32x16_bf16 v[34:49], v[184:187], v[114:117], v[34:49]
	ds_read_b128 v[200:203], v91 offset:16384
	v_exp_f32_e32 v152, v152
	v_exp_f32_e32 v153, v153
	s_waitcnt lgkmcnt(4)
	v_mfma_f32_32x32x16_bf16 v[50:65], v[188:191], v[114:117], v[50:65]
	ds_read_b128 v[204:207], v91 offset:24576
	v_add_f32_e32 v122, v146, v122
	v_add_f32_e32 v122, v147, v122
	v_add_f32_e32 v122, v148, v122
	v_add_f32_e32 v122, v149, v122
	s_waitcnt lgkmcnt(4)
	v_mfma_f32_32x32x16_bf16 v[66:81], v[192:195], v[114:117], v[66:81]
	v_add_f32_e32 v122, v150, v122
	v_add_f32_e32 v122, v151, v122
	v_add_f32_e32 v122, v152, v122
	v_add_f32_e32 v122, v153, v122
	v_cvt_pk_bf16_f32 v118, v146, v147
	v_cvt_pk_bf16_f32 v119, v148, v149
	v_cvt_pk_bf16_f32 v120, v150, v151
	v_cvt_pk_bf16_f32 v121, v152, v153
	s_waitcnt lgkmcnt(3)
	s_nop 0
	v_mfma_f32_32x32x16_bf16 v[18:33], v[196:199], v[118:121], v[18:33]
	ds_read_b128 v[128:131], v92 offset:0
	v_exp_f32_e32 v154, v154
	v_exp_f32_e32 v155, v155
	v_exp_f32_e32 v156, v156
	s_waitcnt lgkmcnt(3)
	v_mfma_f32_32x32x16_bf16 v[34:49], v[216:219], v[118:121], v[34:49]
	ds_read_b128 v[184:187], v92 offset:8192
	v_exp_f32_e32 v157, v157
	v_exp_f32_e32 v158, v158
	v_exp_f32_e32 v159, v159
	v_exp_f32_e32 v160, v160
	s_waitcnt lgkmcnt(3)
	v_mfma_f32_32x32x16_bf16 v[50:65], v[200:203], v[118:121], v[50:65]
	ds_read_b128 v[188:191], v92 offset:16384
	v_exp_f32_e32 v161, v161
	v_add_f32_e32 v122, v154, v122
	v_add_f32_e32 v122, v155, v122
	v_add_f32_e32 v122, v156, v122
	v_add_f32_e32 v122, v157, v122
	v_add_f32_e32 v122, v158, v122
	s_waitcnt lgkmcnt(3)
	v_mfma_f32_32x32x16_bf16 v[66:81], v[204:207], v[118:121], v[66:81]
	ds_read_b128 v[192:195], v92 offset:24576
	v_add_f32_e32 v122, v159, v122
	v_add_f32_e32 v122, v160, v122
	v_add_f32_e32 v122, v161, v122
	v_xor_b32_e32 v82, 0x8000, v82
	v_xor_b32_e32 v83, 0x8000, v83
	v_xor_b32_e32 v84, 0x8000, v84
	v_xor_b32_e32 v85, 0x8000, v85
	v_cvt_pk_bf16_f32 v114, v154, v155
	v_cvt_pk_bf16_f32 v115, v156, v157
	v_cvt_pk_bf16_f32 v116, v158, v159
	v_cvt_pk_bf16_f32 v117, v160, v161
	s_waitcnt lgkmcnt(3)
	s_nop 0
	v_mfma_f32_32x32x16_bf16 v[18:33], v[128:131], v[114:117], v[18:33]
	ds_read_b128 v[196:199], v93 offset:0
	v_exp_f32_e32 v162, v162
	v_exp_f32_e32 v163, v163
	v_exp_f32_e32 v164, v164
	s_waitcnt lgkmcnt(3)
	v_mfma_f32_32x32x16_bf16 v[34:49], v[184:187], v[114:117], v[34:49]
	ds_read_b128 v[216:219], v93 offset:8192
	v_exp_f32_e32 v165, v165
	v_exp_f32_e32 v166, v166
	v_exp_f32_e32 v167, v167
	s_waitcnt lgkmcnt(3)
	v_mfma_f32_32x32x16_bf16 v[50:65], v[188:191], v[114:117], v[50:65]
	ds_read_b128 v[200:203], v93 offset:16384
	v_exp_f32_e32 v168, v168
	v_exp_f32_e32 v169, v169
	v_add_f32_e32 v122, v162, v122
	v_add_f32_e32 v122, v163, v122
	s_waitcnt lgkmcnt(3)
	v_mfma_f32_32x32x16_bf16 v[66:81], v[192:195], v[114:117], v[66:81]
	ds_read_b128 v[204:207], v93 offset:24576
	v_add_f32_e32 v122, v164, v122
	v_add_f32_e32 v122, v165, v122
	v_add_f32_e32 v122, v166, v122
	v_add_f32_e32 v122, v167, v122
	v_add_f32_e32 v122, v168, v122
	v_add_f32_e32 v122, v169, v122
	v_cvt_pk_bf16_f32 v118, v162, v163
	v_cvt_pk_bf16_f32 v119, v164, v165
	v_cvt_pk_bf16_f32 v120, v166, v167
	v_cvt_pk_bf16_f32 v121, v168, v169
	s_waitcnt lgkmcnt(3)
	s_nop 0
	v_mfma_f32_32x32x16_bf16 v[18:33], v[196:199], v[118:121], v[18:33]
	v_xor_b32_e32 v86, 0x8000, v86
	v_xor_b32_e32 v87, 0x8000, v87
	s_waitcnt lgkmcnt(2)
	v_mfma_f32_32x32x16_bf16 v[34:49], v[216:219], v[118:121], v[34:49]
	v_xor_b32_e32 v88, 0x8000, v88
	v_xor_b32_e32 v89, 0x8000, v89
	s_waitcnt lgkmcnt(1)
	v_mfma_f32_32x32x16_bf16 v[50:65], v[200:203], v[118:121], v[50:65]
	v_xor_b32_e32 v90, 0x8000, v90
	v_xor_b32_e32 v91, 0x8000, v91
	s_waitcnt lgkmcnt(0)
	v_mfma_f32_32x32x16_bf16 v[66:81], v[204:207], v[118:121], v[66:81]
	v_xor_b32_e32 v92, 0x8000, v92
	v_xor_b32_e32 v93, 0x8000, v93
	s_waitcnt vmcnt(0)
	s_waitcnt lgkmcnt(0)
	s_barrier
	s_add_i32 s15, s15, 1
	s_cmp_eq_u32 s15, 34
	s_cbranch_scc0 .Lattn_nf_loop
	v_readlane_b32 s64, v175, 0
	v_readlane_b32 s65, v175, 1
	v_readlane_b32 s66, v175, 2
	v_readlane_b32 s67, v175, 3
	v_readlane_b32 s68, v175, 4
	v_readlane_b32 s69, v175, 5
	v_readlane_b32 s70, v175, 6
	v_readlane_b32 s71, v175, 7
	v_readlane_b32 s72, v175, 8
	v_readlane_b32 s73, v175, 9
	v_readlane_b32 s74, v175, 10
	v_readlane_b32 s75, v175, 11
	v_readlane_b32 s76, v175, 12
	v_readlane_b32 s77, v175, 13
	v_readlane_b32 s78, v175, 14
	v_readlane_b32 s79, v175, 15
	s_nop 4
	s_mov_b32 s10, 0x3fb8aa3b
	s_mov_b32 s11, 0xc2ce8ed0
	s_mov_b32 s6, 0x42b17218
	v_cmp_eq_u32_e64 s[40:41], 0, v179
	s_lshl_b32 s30, s14, 1
	v_lshlrev_b32_e32 v196, 3, v178
	v_mov_b32_e32 v197, 0
	v_lshlrev_b32_e32 v198, 4, v179
	v_or3_b32 v198, v198, v177, v180
	v_ashrrev_i32_e32 v199, 31, v198
	v_lshlrev_b64 v[198:199], 11, v[198:199]
	s_mov_b64 s[100:101], 0x18a10000
	v_lshl_add_u64 v[198:199], s[42:43], 0, v[198:199]
	v_lshl_add_u64 v[198:199], v[198:199], 0, s[30:31]
	v_lshl_add_u64 v[198:199], v[198:199], 0, v[196:197]
	v_lshl_add_u64 v[198:199], v[198:199], 0, s[100:101]
	global_load_dwordx2 v[146:147], v[198:199], off
	global_load_dwordx2 v[148:149], v[198:199], off offset:32
	global_load_dwordx2 v[150:151], v[198:199], off offset:64
	global_load_dwordx2 v[152:153], v[198:199], off offset:96
	global_load_dwordx2 v[188:189], v[198:199], off offset:128
	global_load_dwordx2 v[190:191], v[198:199], off offset:160
	global_load_dwordx2 v[192:193], v[198:199], off offset:192
	global_load_dwordx2 v[194:195], v[198:199], off offset:224
	s_mov_b64 s[100:101], exec
	s_and_b64 exec, exec, s[4:5]
	s_cbranch_execz .Lpop_skip
	v_readlane_b32 s14, v255, 22
	v_readlane_b32 s15, v255, 23
	v_mov_b32_e32 v224, 1
	s_nop 4
	global_atomic_add v224, v0, v224, s[14:15] sc0
